# scan worker: next-step LDS operand reads issued ~6 instructions earlier (before the y-partial write), wait counts recomputed
# speedup vs baseline: 1.0069x; 1.0069x over previous
; DI void scan_block(float* ldsf, const u16* __restrict__ R, const u16* __restrict__ KP, const u16* __restrict__ KK, const u16* __restrict__ KKA,
;                    const u16* __restrict__ V, const float* __restrict__ Wd, float* __restrict__ Y, int blk, int wid_k) {
;     ...
;     const float* bp = ldsf + cur * 16 * 336;
;     float* yb = ybuf + cur * 256;
;     if (worker) {
;       typedef float f2 __attribute__((ext_vector_type(2)));
;       f2 Sa = {S0, S1}, Sb = {S2, S3};
;       float4 w4 = *(const float4*)(bp + ks * 4);
;       float4 kk4 = *(const float4*)(bp + 64 + ks * 4);
;       float4 ka4 = *(const float4*)(bp + 128 + ks * 4);
;       float4 kp4 = *(const float4*)(bp + 192 + ks * 4);
;       float4 r4 = *(const float4*)(bp + 256 + ks * 4);
;       float vv = bp[320 + rowl];
;       float yp = 0.f;
; #pragma unroll
;       for (int step = 0; step < 16; ++step) {
;         float4 w4n = w4, kk4n = kk4, ka4n = ka4, kp4n = kp4, r4n = r4; float vvn = vv;
;         if (step + 1 < 16) {
;           const float* sp = bp + (step + 1) * 336;
;           w4n = *(const float4*)(sp + ks * 4);
;           kk4n = *(const float4*)(sp + 64 + ks * 4);
;           ka4n = *(const float4*)(sp + 128 + ks * 4);
;           kp4n = *(const float4*)(sp + 192 + ks * 4);
;           r4n = *(const float4*)(sp + 256 + ks * 4);
;           vvn = sp[320 + rowl];
;         }
;         const f2 kka = {kk4.x, kk4.y}, kkb = {kk4.z, kk4.w}, wa = {w4.x, w4.y}, wb = {w4.z, w4.w};
;         const f2 kaa = {ka4.x, ka4.y}, kab = {ka4.z, ka4.w}, kpa = {kp4.x, kp4.y}, kpb = {kp4.z, kp4.w};
;         const f2 ra = {r4.x, r4.y}, rb = {r4.z, r4.w};
;         const f2 d2 = Sa * kka + Sb * kkb;
;         float d = d2.x + d2.y;
;         const f2 ta = Sa * wa + kpa * vv, tb = Sb * wb + kpb * vv;
;         d = dpp_add<0xB1>(d); yp = dpp_add<0xB1>(yp);
;         d = dpp_add<0x4E>(d); yp = dpp_add<0x4E>(yp);
;         d = dpp_add<0x141>(d); yp = dpp_add<0x141>(yp);
;         d = dpp_add<0x140>(d); yp = dpp_add<0x140>(yp);
;         if (step > 0) yreg = (ks == step - 1) ? yp : yreg;
;         Sa = ta - kaa * d; Sb = tb - kab * d;
;         const f2 y2 = Sa * ra + Sb * rb;
;         yp = y2.x + y2.y;
;         w4 = w4n; kk4 = kk4n; ka4 = ka4n; kp4 = kp4n; r4 = r4n; vv = vvn;
;       }
.LBB0_1288:
	s_and_b32 s66, s62, 1
	s_mul_i32 s63, s66, 0x5400
	s_add_i32 s67, s63, 0
	s_mul_i32 s63, s66, 0xffffb000
	s_add_i32 s63, s67, s63
	s_and_saveexec_b64 s[64:65], s[6:7]
	s_cbranch_execz .LBB0_1290
	s_lshl_b32 s63, s66, 14
	s_add_i32 s63, s63, 0x10000
	v_lshl_add_u32 v99, v69, 2, s63
	v_lshl_add_u32 v79, v70, 2, s67
	ds_read_b128 v[18:21], v79
	ds_read_b128 v[22:25], v79 offset:256
	ds_read_b128 v[26:29], v79 offset:512
	ds_read_b128 v[30:33], v79 offset:768
	ds_read_b128 v[34:37], v79 offset:1024
	v_add_u32_e32 v78, s67, v76
	ds_read_b32 v68, v78 offset:1280
	ds_read_b128 v[38:41], v79 offset:1344
	ds_read_b128 v[42:45], v79 offset:1600
	ds_read_b128 v[46:49], v79 offset:1856
	ds_read_b128 v[50:53], v79 offset:2112
	ds_read_b128 v[64:67], v79 offset:2368
	ds_read_b32 v80, v78 offset:2624
	s_waitcnt lgkmcnt(10)
	v_pk_mul_f32 v[22:23], v[14:15], v[22:23]
	v_pk_fma_f32 v[22:23], v[16:17], v[24:25], v[22:23]
	s_nop 0
	v_add_f32_e32 v24, v22, v23
	s_waitcnt lgkmcnt(6)
	v_pk_mul_f32 v[22:23], v[30:31], v[68:69] op_sel_hi:[1,0]
	s_nop 0
	v_pk_fma_f32 v[14:15], v[14:15], v[18:19], v[22:23]
	v_pk_mul_f32 v[18:19], v[32:33], v[68:69] op_sel_hi:[1,0]
	s_nop 0
	v_pk_fma_f32 v[16:17], v[16:17], v[20:21], v[18:19]
	v_add_f32_dpp v18, v24, v24 quad_perm:[1,0,3,2] row_mask:0xf bank_mask:0xf bound_ctrl:1
	s_nop 1
	v_add_f32_dpp v18, v18, v18 quad_perm:[2,3,0,1] row_mask:0xf bank_mask:0xf bound_ctrl:1
	s_nop 1
	v_add_f32_dpp v18, v18, v18 row_half_mirror row_mask:0xf bank_mask:0xf bound_ctrl:1
	s_nop 1
	v_add_f32_dpp v18, v18, v18 row_mirror row_mask:0xf bank_mask:0xf bound_ctrl:1
	v_pk_fma_f32 v[84:85], v[28:29], v[18:19], v[16:17] op_sel_hi:[1,0,1] neg_lo:[1,0,0] neg_hi:[1,0,0]
	v_pk_fma_f32 v[82:83], v[26:27], v[18:19], v[14:15] op_sel_hi:[1,0,1] neg_lo:[1,0,0] neg_hi:[1,0,0]
	v_pk_mul_f32 v[14:15], v[36:37], v[84:85]
	s_waitcnt lgkmcnt(5)
	v_pk_mul_f32 v[36:37], v[40:41], v[84:85]
	v_pk_fma_f32 v[14:15], v[34:35], v[82:83], v[14:15]
	s_waitcnt lgkmcnt(4)
	v_pk_mul_f32 v[34:35], v[42:43], v[82:83]
	v_add_f32_e32 v81, v14, v15
	ds_read_b128 v[14:17], v79 offset:2688
	ds_read_b128 v[18:21], v79 offset:2944
	ds_read_b128 v[22:25], v79 offset:3200
	ds_read_b128 v[26:29], v79 offset:3456
	ds_read_b128 v[30:33], v79 offset:3712
	ds_read_b32 v68, v78 offset:3968
	ds_write_b32 v99, v81
	v_pk_fma_f32 v[34:35], v[44:45], v[84:85], v[34:35]
	s_waitcnt lgkmcnt(7)
	v_pk_fma_f32 v[36:37], v[52:53], v[80:81], v[36:37] op_sel_hi:[1,0,1]
	v_add_f32_e32 v42, v34, v35
	v_pk_mul_f32 v[34:35], v[38:39], v[82:83]
	s_nop 0
	v_add_f32_dpp v38, v42, v42 quad_perm:[1,0,3,2] row_mask:0xf bank_mask:0xf bound_ctrl:1
	v_pk_fma_f32 v[34:35], v[50:51], v[80:81], v[34:35] op_sel_hi:[1,0,1]
	s_nop 0
	v_add_f32_dpp v38, v38, v38 quad_perm:[2,3,0,1] row_mask:0xf bank_mask:0xf bound_ctrl:1
	s_nop 1
	v_add_f32_dpp v38, v38, v38 row_half_mirror row_mask:0xf bank_mask:0xf bound_ctrl:1
	s_nop 0
	s_nop 0
	v_add_f32_dpp v38, v38, v38 row_mirror row_mask:0xf bank_mask:0xf bound_ctrl:1
	v_pk_fma_f32 v[80:81], v[46:47], v[38:39], v[34:35] op_sel_hi:[1,0,1] neg_lo:[1,0,0] neg_hi:[1,0,0]
	v_pk_fma_f32 v[82:83], v[48:49], v[38:39], v[36:37] op_sel_hi:[1,0,1] neg_lo:[1,0,0] neg_hi:[1,0,0]
	s_waitcnt lgkmcnt(5)
	v_pk_mul_f32 v[18:19], v[18:19], v[80:81]
	v_pk_mul_f32 v[34:35], v[66:67], v[82:83]
	v_pk_fma_f32 v[18:19], v[20:21], v[82:83], v[18:19]
	v_pk_fma_f32 v[34:35], v[64:65], v[80:81], v[34:35]
	v_add_f32_e32 v18, v18, v19
	v_add_f32_e32 v64, v34, v35
	ds_read_b128 v[34:37], v79 offset:4032
	ds_read_b128 v[38:41], v79 offset:4288
	ds_read_b128 v[42:45], v79 offset:4544
	ds_read_b128 v[46:49], v79 offset:4800
	ds_read_b128 v[50:53], v79 offset:5056
	ds_read_b32 v0, v78 offset:5312
	ds_write_b32 v99, v64 offset:1024
	v_pk_mul_f32 v[14:15], v[14:15], v[80:81]
	v_add_f32_dpp v18, v18, v18 quad_perm:[1,0,3,2] row_mask:0xf bank_mask:0xf bound_ctrl:1
	s_nop 1
	v_add_f32_dpp v18, v18, v18 quad_perm:[2,3,0,1] row_mask:0xf bank_mask:0xf bound_ctrl:1
	s_nop 1
	v_add_f32_dpp v18, v18, v18 row_half_mirror row_mask:0xf bank_mask:0xf bound_ctrl:1
	s_waitcnt lgkmcnt(8)
	v_pk_fma_f32 v[14:15], v[26:27], v[68:69], v[14:15] op_sel_hi:[1,0,1]
	v_pk_mul_f32 v[16:17], v[16:17], v[82:83]
	v_add_f32_dpp v18, v18, v18 row_mirror row_mask:0xf bank_mask:0xf bound_ctrl:1
	v_pk_fma_f32 v[16:17], v[28:29], v[68:69], v[16:17] op_sel_hi:[1,0,1]
	v_pk_fma_f32 v[64:65], v[22:23], v[18:19], v[14:15] op_sel_hi:[1,0,1] neg_lo:[1,0,0] neg_hi:[1,0,0]
	v_pk_fma_f32 v[66:67], v[24:25], v[18:19], v[16:17] op_sel_hi:[1,0,1] neg_lo:[1,0,0] neg_hi:[1,0,0]
	s_waitcnt lgkmcnt(5)
	v_pk_mul_f32 v[38:39], v[38:39], v[64:65]
	v_pk_mul_f32 v[34:35], v[34:35], v[64:65]
	v_pk_fma_f32 v[38:39], v[40:41], v[66:67], v[38:39]
	v_pk_mul_f32 v[36:37], v[36:37], v[66:67]
	v_add_f32_e32 v38, v38, v39
	s_waitcnt lgkmcnt(1)
	v_pk_fma_f32 v[34:35], v[46:47], v[0:1], v[34:35] op_sel_hi:[1,0,1]
	v_pk_fma_f32 v[36:37], v[48:49], v[0:1], v[36:37] op_sel_hi:[1,0,1]
	v_add_f32_dpp v0, v38, v38 quad_perm:[1,0,3,2] row_mask:0xf bank_mask:0xf bound_ctrl:1
	v_pk_mul_f32 v[14:15], v[32:33], v[66:67]
	s_nop 0
	v_add_f32_dpp v0, v0, v0 quad_perm:[2,3,0,1] row_mask:0xf bank_mask:0xf bound_ctrl:1
	v_pk_fma_f32 v[14:15], v[30:31], v[64:65], v[14:15]
	s_nop 0
	v_add_f32_dpp v0, v0, v0 row_half_mirror row_mask:0xf bank_mask:0xf bound_ctrl:1
	v_add_f32_e32 v81, v14, v15
	ds_read_b128 v[14:17], v79 offset:5376
	ds_read_b128 v[18:21], v79 offset:5632
	ds_read_b128 v[22:25], v79 offset:5888
	ds_read_b128 v[26:29], v79 offset:6144
	ds_read_b128 v[30:33], v79 offset:6400
	ds_read_b32 v68, v78 offset:6656
	ds_write_b32 v99, v81 offset:2048
	v_add_f32_dpp v0, v0, v0 row_mirror row_mask:0xf bank_mask:0xf bound_ctrl:1
	v_pk_fma_f32 v[64:65], v[42:43], v[0:1], v[34:35] op_sel_hi:[1,0,1] neg_lo:[1,0,0] neg_hi:[1,0,0]
	v_pk_fma_f32 v[66:67], v[44:45], v[0:1], v[36:37] op_sel_hi:[1,0,1] neg_lo:[1,0,0] neg_hi:[1,0,0]
	s_waitcnt lgkmcnt(5)
; DI void scan_block(float* ldsf, const u16* __restrict__ R, const u16* __restrict__ KP, const u16* __restrict__ KK, const u16* __restrict__ KKA,
;                    const u16* __restrict__ V, const float* __restrict__ Wd, float* __restrict__ Y, int blk, int wid_k) {
;     ...
;       for (int step = 0; step < 16; ++step) {
;         float4 w4n = w4, kk4n = kk4, ka4n = ka4, kp4n = kp4, r4n = r4; float vvn = vv;
;         if (step + 1 < 16) {
;           const float* sp = bp + (step + 1) * 336;
;           w4n = *(const float4*)(sp + ks * 4);
;           kk4n = *(const float4*)(sp + 64 + ks * 4);
;           ka4n = *(const float4*)(sp + 128 + ks * 4);
;           kp4n = *(const float4*)(sp + 192 + ks * 4);
;           r4n = *(const float4*)(sp + 256 + ks * 4);
;           vvn = sp[320 + rowl];
;         }
;         const f2 kka = {kk4.x, kk4.y}, kkb = {kk4.z, kk4.w}, wa = {w4.x, w4.y}, wb = {w4.z, w4.w};
;         const f2 kaa = {ka4.x, ka4.y}, kab = {ka4.z, ka4.w}, kpa = {kp4.x, kp4.y}, kpb = {kp4.z, kp4.w};
;         const f2 ra = {r4.x, r4.y}, rb = {r4.z, r4.w};
;         const f2 d2 = Sa * kka + Sb * kkb;
;         float d = d2.x + d2.y;
;         const f2 ta = Sa * wa + kpa * vv, tb = Sb * wb + kpb * vv;
;         d = dpp_add<0xB1>(d); yp = dpp_add<0xB1>(yp);
;         d = dpp_add<0x4E>(d); yp = dpp_add<0x4E>(yp);
;         d = dpp_add<0x141>(d); yp = dpp_add<0x141>(yp);
;         d = dpp_add<0x140>(d); yp = dpp_add<0x140>(yp);
;         if (step > 0) yreg = (ks == step - 1) ? yp : yreg;
;         Sa = ta - kaa * d; Sb = tb - kab * d;
;         const f2 y2 = Sa * ra + Sb * rb;
;         yp = y2.x + y2.y;
;         w4 = w4n; kk4 = kk4n; ka4 = ka4n; kp4 = kp4n; r4 = r4n; vv = vvn;
;       }
	v_pk_mul_f32 v[18:19], v[18:19], v[64:65]
	v_pk_mul_f32 v[34:35], v[52:53], v[66:67]
	v_pk_fma_f32 v[18:19], v[20:21], v[66:67], v[18:19]
	v_pk_fma_f32 v[34:35], v[50:51], v[64:65], v[34:35]
	v_add_f32_e32 v18, v18, v19
	v_add_f32_e32 v0, v34, v35
	ds_read_b128 v[34:37], v79 offset:6720
	ds_read_b128 v[38:41], v79 offset:6976
	ds_read_b128 v[42:45], v79 offset:7232
	ds_read_b128 v[46:49], v79 offset:7488
	ds_read_b128 v[50:53], v79 offset:7744
	ds_read_b32 v80, v78 offset:8000
	ds_write_b32 v99, v0 offset:3072
	v_add_f32_dpp v18, v18, v18 quad_perm:[1,0,3,2] row_mask:0xf bank_mask:0xf bound_ctrl:1
	s_nop 1
	v_add_f32_dpp v18, v18, v18 quad_perm:[2,3,0,1] row_mask:0xf bank_mask:0xf bound_ctrl:1
	v_pk_mul_f32 v[14:15], v[14:15], v[64:65]
	v_pk_mul_f32 v[16:17], v[16:17], v[66:67]
	v_add_f32_dpp v18, v18, v18 row_half_mirror row_mask:0xf bank_mask:0xf bound_ctrl:1
	s_waitcnt lgkmcnt(8)
	v_pk_fma_f32 v[14:15], v[26:27], v[68:69], v[14:15] op_sel_hi:[1,0,1]
	v_pk_fma_f32 v[16:17], v[28:29], v[68:69], v[16:17] op_sel_hi:[1,0,1]
	v_add_f32_dpp v0, v18, v18 row_mirror row_mask:0xf bank_mask:0xf bound_ctrl:1
	v_pk_fma_f32 v[64:65], v[22:23], v[0:1], v[14:15] op_sel_hi:[1,0,1] neg_lo:[1,0,0] neg_hi:[1,0,0]
	v_pk_fma_f32 v[66:67], v[24:25], v[0:1], v[16:17] op_sel_hi:[1,0,1] neg_lo:[1,0,0] neg_hi:[1,0,0]
	ds_read_b128 v[22:25], v79 offset:8064
	s_waitcnt lgkmcnt(6)
	v_pk_mul_f32 v[38:39], v[38:39], v[64:65]
	v_pk_mul_f32 v[14:15], v[32:33], v[66:67]
	v_pk_fma_f32 v[14:15], v[30:31], v[64:65], v[14:15]
	ds_read_b128 v[30:33], v79 offset:8320
	v_pk_fma_f32 v[38:39], v[40:41], v[66:67], v[38:39]
	v_add_f32_e32 v81, v14, v15
	ds_read_b128 v[14:17], v79 offset:8576
	ds_read_b128 v[26:29], v79 offset:8832
	ds_read_b128 v[18:21], v79 offset:9088
	ds_read_b32 v0, v78 offset:9344
	ds_write_b32 v99, v81 offset:4096
	v_add_f32_e32 v38, v38, v39
	v_pk_mul_f32 v[34:35], v[34:35], v[64:65]
	s_nop 0
	v_add_f32_dpp v38, v38, v38 quad_perm:[1,0,3,2] row_mask:0xf bank_mask:0xf bound_ctrl:1
	s_nop 1
	v_add_f32_dpp v38, v38, v38 quad_perm:[2,3,0,1] row_mask:0xf bank_mask:0xf bound_ctrl:1
	s_waitcnt lgkmcnt(8)
	v_pk_fma_f32 v[34:35], v[46:47], v[80:81], v[34:35] op_sel_hi:[1,0,1]
	v_add_f32_dpp v38, v38, v38 row_half_mirror row_mask:0xf bank_mask:0xf bound_ctrl:1
	v_pk_mul_f32 v[36:37], v[36:37], v[66:67]
	s_nop 0
	v_add_f32_dpp v38, v38, v38 row_mirror row_mask:0xf bank_mask:0xf bound_ctrl:1
	v_pk_fma_f32 v[36:37], v[48:49], v[80:81], v[36:37] op_sel_hi:[1,0,1]
	v_pk_fma_f32 v[66:67], v[42:43], v[38:39], v[34:35] op_sel_hi:[1,0,1] neg_lo:[1,0,0] neg_hi:[1,0,0]
	v_pk_fma_f32 v[64:65], v[44:45], v[38:39], v[36:37] op_sel_hi:[1,0,1] neg_lo:[1,0,0] neg_hi:[1,0,0]
	ds_read_b128 v[42:45], v79 offset:9408
	s_waitcnt lgkmcnt(6)
	v_pk_mul_f32 v[30:31], v[30:31], v[66:67]
	v_pk_mul_f32 v[22:23], v[22:23], v[66:67]
	v_pk_fma_f32 v[30:31], v[32:33], v[64:65], v[30:31]
	v_pk_mul_f32 v[24:25], v[24:25], v[64:65]
	v_add_f32_e32 v30, v30, v31
	s_waitcnt lgkmcnt(2)
	v_pk_fma_f32 v[22:23], v[26:27], v[0:1], v[22:23] op_sel_hi:[1,0,1]
	v_pk_fma_f32 v[24:25], v[28:29], v[0:1], v[24:25] op_sel_hi:[1,0,1]
	v_add_f32_dpp v0, v30, v30 quad_perm:[1,0,3,2] row_mask:0xf bank_mask:0xf bound_ctrl:1
	v_pk_mul_f32 v[34:35], v[52:53], v[64:65]
	s_nop 0
	v_add_f32_dpp v0, v0, v0 quad_perm:[2,3,0,1] row_mask:0xf bank_mask:0xf bound_ctrl:1
	v_pk_fma_f32 v[34:35], v[50:51], v[66:67], v[34:35]
	ds_read_b128 v[50:53], v79 offset:9664
	s_nop 0
	v_add_f32_dpp v0, v0, v0 row_half_mirror row_mask:0xf bank_mask:0xf bound_ctrl:1
	v_add_f32_e32 v81, v34, v35
	ds_read_b128 v[34:37], v79 offset:9920
	ds_read_b128 v[46:49], v79 offset:10176
	ds_read_b128 v[38:41], v79 offset:10432
	ds_read_b32 v68, v78 offset:10688
	ds_write_b32 v99, v81 offset:5120
	v_add_f32_dpp v0, v0, v0 row_mirror row_mask:0xf bank_mask:0xf bound_ctrl:1
	v_pk_fma_f32 v[64:65], v[14:15], v[0:1], v[22:23] op_sel_hi:[1,0,1] neg_lo:[1,0,0] neg_hi:[1,0,0]
	v_pk_fma_f32 v[66:67], v[16:17], v[0:1], v[24:25] op_sel_hi:[1,0,1] neg_lo:[1,0,0] neg_hi:[1,0,0]
	s_waitcnt lgkmcnt(5)
	v_pk_mul_f32 v[50:51], v[50:51], v[64:65]
	v_pk_mul_f32 v[14:15], v[20:21], v[66:67]
	v_pk_fma_f32 v[50:51], v[52:53], v[66:67], v[50:51]
	v_pk_fma_f32 v[14:15], v[18:19], v[64:65], v[14:15]
	v_add_f32_e32 v81, v14, v15
	ds_read_b128 v[14:17], v79 offset:10752
	ds_read_b128 v[18:21], v79 offset:11008
	ds_read_b128 v[22:25], v79 offset:11264
	ds_read_b128 v[26:29], v79 offset:11520
	ds_read_b128 v[30:33], v79 offset:11776
	ds_read_b32 v0, v78 offset:12032
	ds_write_b32 v99, v81 offset:6144
	v_add_f32_e32 v50, v50, v51
	v_pk_mul_f32 v[42:43], v[42:43], v[64:65]
	s_waitcnt lgkmcnt(8)
	v_pk_fma_f32 v[42:43], v[46:47], v[68:69], v[42:43] op_sel_hi:[1,0,1]
	v_add_f32_dpp v46, v50, v50 quad_perm:[1,0,3,2] row_mask:0xf bank_mask:0xf bound_ctrl:1
	s_nop 1
	v_add_f32_dpp v46, v46, v46 quad_perm:[2,3,0,1] row_mask:0xf bank_mask:0xf bound_ctrl:1
	s_nop 1
	v_add_f32_dpp v46, v46, v46 row_half_mirror row_mask:0xf bank_mask:0xf bound_ctrl:1
	v_pk_mul_f32 v[44:45], v[44:45], v[66:67]
	s_nop 0
	v_add_f32_dpp v46, v46, v46 row_mirror row_mask:0xf bank_mask:0xf bound_ctrl:1
	v_pk_fma_f32 v[44:45], v[48:49], v[68:69], v[44:45] op_sel_hi:[1,0,1]
	v_pk_fma_f32 v[64:65], v[34:35], v[46:47], v[42:43] op_sel_hi:[1,0,1] neg_lo:[1,0,0] neg_hi:[1,0,0]
	v_pk_fma_f32 v[66:67], v[36:37], v[46:47], v[44:45] op_sel_hi:[1,0,1] neg_lo:[1,0,0] neg_hi:[1,0,0]
	s_waitcnt lgkmcnt(5)
	v_pk_mul_f32 v[18:19], v[18:19], v[64:65]
	v_pk_mul_f32 v[14:15], v[14:15], v[64:65]
	v_pk_fma_f32 v[18:19], v[20:21], v[66:67], v[18:19]
	v_pk_mul_f32 v[16:17], v[16:17], v[66:67]
	v_add_f32_e32 v18, v18, v19
	s_waitcnt lgkmcnt(1)
; DI void scan_block(float* ldsf, const u16* __restrict__ R, const u16* __restrict__ KP, const u16* __restrict__ KK, const u16* __restrict__ KKA,
;                    const u16* __restrict__ V, const float* __restrict__ Wd, float* __restrict__ Y, int blk, int wid_k) {
;     ...
;       for (int step = 0; step < 16; ++step) {
;         float4 w4n = w4, kk4n = kk4, ka4n = ka4, kp4n = kp4, r4n = r4; float vvn = vv;
;         if (step + 1 < 16) {
;           const float* sp = bp + (step + 1) * 336;
;           w4n = *(const float4*)(sp + ks * 4);
;           kk4n = *(const float4*)(sp + 64 + ks * 4);
;           ka4n = *(const float4*)(sp + 128 + ks * 4);
;           kp4n = *(const float4*)(sp + 192 + ks * 4);
;           r4n = *(const float4*)(sp + 256 + ks * 4);
;           vvn = sp[320 + rowl];
;         }
;         const f2 kka = {kk4.x, kk4.y}, kkb = {kk4.z, kk4.w}, wa = {w4.x, w4.y}, wb = {w4.z, w4.w};
;         const f2 kaa = {ka4.x, ka4.y}, kab = {ka4.z, ka4.w}, kpa = {kp4.x, kp4.y}, kpb = {kp4.z, kp4.w};
;         const f2 ra = {r4.x, r4.y}, rb = {r4.z, r4.w};
;         const f2 d2 = Sa * kka + Sb * kkb;
;         float d = d2.x + d2.y;
;         const f2 ta = Sa * wa + kpa * vv, tb = Sb * wb + kpb * vv;
;         d = dpp_add<0xB1>(d); yp = dpp_add<0xB1>(yp);
;         d = dpp_add<0x4E>(d); yp = dpp_add<0x4E>(yp);
;         d = dpp_add<0x141>(d); yp = dpp_add<0x141>(yp);
;         d = dpp_add<0x140>(d); yp = dpp_add<0x140>(yp);
;         if (step > 0) yreg = (ks == step - 1) ? yp : yreg;
;         Sa = ta - kaa * d; Sb = tb - kab * d;
;         const f2 y2 = Sa * ra + Sb * rb;
;         yp = y2.x + y2.y;
;         w4 = w4n; kk4 = kk4n; ka4 = ka4n; kp4 = kp4n; r4 = r4n; vv = vvn;
;       }
	v_pk_fma_f32 v[14:15], v[26:27], v[0:1], v[14:15] op_sel_hi:[1,0,1]
	v_pk_fma_f32 v[16:17], v[28:29], v[0:1], v[16:17] op_sel_hi:[1,0,1]
	v_add_f32_dpp v0, v18, v18 quad_perm:[1,0,3,2] row_mask:0xf bank_mask:0xf bound_ctrl:1
	v_pk_mul_f32 v[34:35], v[40:41], v[66:67]
	s_nop 0
	v_add_f32_dpp v0, v0, v0 quad_perm:[2,3,0,1] row_mask:0xf bank_mask:0xf bound_ctrl:1
	v_pk_fma_f32 v[34:35], v[38:39], v[64:65], v[34:35]
	s_nop 0
	v_add_f32_dpp v0, v0, v0 row_half_mirror row_mask:0xf bank_mask:0xf bound_ctrl:1
	v_add_f32_e32 v81, v34, v35
	ds_read_b128 v[34:37], v79 offset:12096
	ds_read_b128 v[38:41], v79 offset:12352
	ds_read_b128 v[42:45], v79 offset:12608
	ds_read_b128 v[46:49], v79 offset:12864
	ds_read_b128 v[50:53], v79 offset:13120
	ds_read_b32 v68, v78 offset:13376
	ds_write_b32 v99, v81 offset:7168
	v_add_f32_dpp v0, v0, v0 row_mirror row_mask:0xf bank_mask:0xf bound_ctrl:1
	v_pk_fma_f32 v[64:65], v[22:23], v[0:1], v[14:15] op_sel_hi:[1,0,1] neg_lo:[1,0,0] neg_hi:[1,0,0]
	v_pk_fma_f32 v[66:67], v[24:25], v[0:1], v[16:17] op_sel_hi:[1,0,1] neg_lo:[1,0,0] neg_hi:[1,0,0]
	s_waitcnt lgkmcnt(5)
	v_pk_mul_f32 v[38:39], v[38:39], v[64:65]
	v_pk_mul_f32 v[14:15], v[32:33], v[66:67]
	v_pk_fma_f32 v[38:39], v[40:41], v[66:67], v[38:39]
	v_pk_fma_f32 v[14:15], v[30:31], v[64:65], v[14:15]
	v_add_f32_e32 v81, v14, v15
	ds_read_b128 v[14:17], v79 offset:13440
	ds_read_b128 v[18:21], v79 offset:13696
	ds_read_b128 v[22:25], v79 offset:13952
	ds_read_b128 v[26:29], v79 offset:14208
	ds_read_b128 v[30:33], v79 offset:14464
	ds_read_b32 v0, v78 offset:14720
	ds_write_b32 v99, v81 offset:8192
	v_add_f32_e32 v38, v38, v39
	s_nop 1
	v_add_f32_dpp v38, v38, v38 quad_perm:[1,0,3,2] row_mask:0xf bank_mask:0xf bound_ctrl:1
	s_nop 1
	v_add_f32_dpp v38, v38, v38 quad_perm:[2,3,0,1] row_mask:0xf bank_mask:0xf bound_ctrl:1
	v_pk_mul_f32 v[34:35], v[34:35], v[64:65]
	s_nop 0
	v_add_f32_dpp v38, v38, v38 row_half_mirror row_mask:0xf bank_mask:0xf bound_ctrl:1
	s_waitcnt lgkmcnt(8)
	v_pk_fma_f32 v[34:35], v[46:47], v[68:69], v[34:35] op_sel_hi:[1,0,1]
	v_pk_mul_f32 v[36:37], v[36:37], v[66:67]
	v_add_f32_dpp v38, v38, v38 row_mirror row_mask:0xf bank_mask:0xf bound_ctrl:1
	v_pk_fma_f32 v[36:37], v[48:49], v[68:69], v[36:37] op_sel_hi:[1,0,1]
	v_pk_fma_f32 v[64:65], v[42:43], v[38:39], v[34:35] op_sel_hi:[1,0,1] neg_lo:[1,0,0] neg_hi:[1,0,0]
	v_pk_fma_f32 v[66:67], v[44:45], v[38:39], v[36:37] op_sel_hi:[1,0,1] neg_lo:[1,0,0] neg_hi:[1,0,0]
	s_waitcnt lgkmcnt(5)
	v_pk_mul_f32 v[18:19], v[18:19], v[64:65]
	v_pk_mul_f32 v[14:15], v[14:15], v[64:65]
	v_pk_fma_f32 v[18:19], v[20:21], v[66:67], v[18:19]
	v_pk_mul_f32 v[16:17], v[16:17], v[66:67]
	v_add_f32_e32 v18, v18, v19
	s_waitcnt lgkmcnt(1)
	v_pk_fma_f32 v[14:15], v[26:27], v[0:1], v[14:15] op_sel_hi:[1,0,1]
	v_pk_fma_f32 v[16:17], v[28:29], v[0:1], v[16:17] op_sel_hi:[1,0,1]
	v_add_f32_dpp v0, v18, v18 quad_perm:[1,0,3,2] row_mask:0xf bank_mask:0xf bound_ctrl:1
	v_pk_mul_f32 v[34:35], v[52:53], v[66:67]
	s_nop 0
	v_add_f32_dpp v0, v0, v0 quad_perm:[2,3,0,1] row_mask:0xf bank_mask:0xf bound_ctrl:1
	v_pk_fma_f32 v[34:35], v[50:51], v[64:65], v[34:35]
	s_nop 0
	v_add_f32_dpp v0, v0, v0 row_half_mirror row_mask:0xf bank_mask:0xf bound_ctrl:1
	v_add_f32_e32 v81, v34, v35
	ds_read_b128 v[34:37], v79 offset:14784
	ds_read_b128 v[38:41], v79 offset:15040
	ds_read_b128 v[42:45], v79 offset:15296
	ds_read_b128 v[46:49], v79 offset:15552
	ds_read_b128 v[50:53], v79 offset:15808
	ds_read_b32 v68, v78 offset:16064
	ds_write_b32 v99, v81 offset:9216
	v_add_f32_dpp v0, v0, v0 row_mirror row_mask:0xf bank_mask:0xf bound_ctrl:1
	v_pk_fma_f32 v[64:65], v[22:23], v[0:1], v[14:15] op_sel_hi:[1,0,1] neg_lo:[1,0,0] neg_hi:[1,0,0]
	v_pk_fma_f32 v[66:67], v[24:25], v[0:1], v[16:17] op_sel_hi:[1,0,1] neg_lo:[1,0,0] neg_hi:[1,0,0]
	s_waitcnt lgkmcnt(5)
	v_pk_mul_f32 v[38:39], v[38:39], v[64:65]
	v_pk_mul_f32 v[14:15], v[32:33], v[66:67]
	v_pk_fma_f32 v[38:39], v[40:41], v[66:67], v[38:39]
	v_pk_fma_f32 v[14:15], v[30:31], v[64:65], v[14:15]
	v_add_f32_e32 v81, v14, v15
	ds_read_b128 v[14:17], v79 offset:16128
	ds_read_b128 v[18:21], v79 offset:16384
	ds_read_b128 v[22:25], v79 offset:16640
	ds_read_b128 v[26:29], v79 offset:16896
	ds_read_b128 v[30:33], v79 offset:17152
	ds_read_b32 v0, v78 offset:17408
	ds_write_b32 v99, v81 offset:10240
	v_add_f32_e32 v38, v38, v39
	s_nop 1
	v_add_f32_dpp v38, v38, v38 quad_perm:[1,0,3,2] row_mask:0xf bank_mask:0xf bound_ctrl:1
	s_nop 1
	v_add_f32_dpp v38, v38, v38 quad_perm:[2,3,0,1] row_mask:0xf bank_mask:0xf bound_ctrl:1
	v_pk_mul_f32 v[34:35], v[34:35], v[64:65]
	s_nop 0
	v_add_f32_dpp v38, v38, v38 row_half_mirror row_mask:0xf bank_mask:0xf bound_ctrl:1
	s_waitcnt lgkmcnt(8)
	v_pk_fma_f32 v[34:35], v[46:47], v[68:69], v[34:35] op_sel_hi:[1,0,1]
	v_pk_mul_f32 v[36:37], v[36:37], v[66:67]
	v_add_f32_dpp v38, v38, v38 row_mirror row_mask:0xf bank_mask:0xf bound_ctrl:1
	v_pk_fma_f32 v[36:37], v[48:49], v[68:69], v[36:37] op_sel_hi:[1,0,1]
	v_pk_fma_f32 v[64:65], v[42:43], v[38:39], v[34:35] op_sel_hi:[1,0,1] neg_lo:[1,0,0] neg_hi:[1,0,0]
	v_pk_fma_f32 v[66:67], v[44:45], v[38:39], v[36:37] op_sel_hi:[1,0,1] neg_lo:[1,0,0] neg_hi:[1,0,0]
	s_waitcnt lgkmcnt(5)
	v_pk_mul_f32 v[18:19], v[18:19], v[64:65]
	v_pk_mul_f32 v[14:15], v[14:15], v[64:65]
	v_pk_fma_f32 v[18:19], v[20:21], v[66:67], v[18:19]
	v_pk_mul_f32 v[16:17], v[16:17], v[66:67]
	v_add_f32_e32 v18, v18, v19
	s_waitcnt lgkmcnt(1)
; DI void scan_block(float* ldsf, const u16* __restrict__ R, const u16* __restrict__ KP, const u16* __restrict__ KK, const u16* __restrict__ KKA,
;                    const u16* __restrict__ V, const float* __restrict__ Wd, float* __restrict__ Y, int blk, int wid_k) {
;     ...
;       for (int step = 0; step < 16; ++step) {
;         float4 w4n = w4, kk4n = kk4, ka4n = ka4, kp4n = kp4, r4n = r4; float vvn = vv;
;         if (step + 1 < 16) {
;           const float* sp = bp + (step + 1) * 336;
;           w4n = *(const float4*)(sp + ks * 4);
;           kk4n = *(const float4*)(sp + 64 + ks * 4);
;           ka4n = *(const float4*)(sp + 128 + ks * 4);
;           kp4n = *(const float4*)(sp + 192 + ks * 4);
;           r4n = *(const float4*)(sp + 256 + ks * 4);
;           vvn = sp[320 + rowl];
;         }
;         const f2 kka = {kk4.x, kk4.y}, kkb = {kk4.z, kk4.w}, wa = {w4.x, w4.y}, wb = {w4.z, w4.w};
;         const f2 kaa = {ka4.x, ka4.y}, kab = {ka4.z, ka4.w}, kpa = {kp4.x, kp4.y}, kpb = {kp4.z, kp4.w};
;         const f2 ra = {r4.x, r4.y}, rb = {r4.z, r4.w};
;         const f2 d2 = Sa * kka + Sb * kkb;
;         float d = d2.x + d2.y;
;         const f2 ta = Sa * wa + kpa * vv, tb = Sb * wb + kpb * vv;
;         d = dpp_add<0xB1>(d); yp = dpp_add<0xB1>(yp);
;         d = dpp_add<0x4E>(d); yp = dpp_add<0x4E>(yp);
;         d = dpp_add<0x141>(d); yp = dpp_add<0x141>(yp);
;         d = dpp_add<0x140>(d); yp = dpp_add<0x140>(yp);
;         if (step > 0) yreg = (ks == step - 1) ? yp : yreg;
;         Sa = ta - kaa * d; Sb = tb - kab * d;
;         const f2 y2 = Sa * ra + Sb * rb;
;         yp = y2.x + y2.y;
;         w4 = w4n; kk4 = kk4n; ka4 = ka4n; kp4 = kp4n; r4 = r4n; vv = vvn;
;       }
;       yp = reduce16(yp);
;       yreg = (ks == 15) ? yp : yreg;
;       S0 = Sa.x; S1 = Sa.y; S2 = Sb.x; S3 = Sb.y;
;       yb[ks * 16 + rowl] = yreg;
	v_pk_fma_f32 v[14:15], v[26:27], v[0:1], v[14:15] op_sel_hi:[1,0,1]
	v_pk_fma_f32 v[16:17], v[28:29], v[0:1], v[16:17] op_sel_hi:[1,0,1]
	v_add_f32_dpp v0, v18, v18 quad_perm:[1,0,3,2] row_mask:0xf bank_mask:0xf bound_ctrl:1
	v_pk_mul_f32 v[34:35], v[52:53], v[66:67]
	s_nop 0
	v_add_f32_dpp v0, v0, v0 quad_perm:[2,3,0,1] row_mask:0xf bank_mask:0xf bound_ctrl:1
	v_pk_fma_f32 v[34:35], v[50:51], v[64:65], v[34:35]
	s_nop 0
	v_add_f32_dpp v0, v0, v0 row_half_mirror row_mask:0xf bank_mask:0xf bound_ctrl:1
	v_add_f32_e32 v81, v34, v35
	ds_read_b128 v[34:37], v79 offset:17472
	ds_read_b128 v[38:41], v79 offset:17728
	ds_read_b128 v[42:45], v79 offset:17984
	ds_read_b128 v[46:49], v79 offset:18240
	ds_read_b128 v[50:53], v79 offset:18496
	ds_read_b32 v68, v78 offset:18752
	ds_write_b32 v99, v81 offset:11264
	v_add_f32_dpp v0, v0, v0 row_mirror row_mask:0xf bank_mask:0xf bound_ctrl:1
	v_pk_fma_f32 v[64:65], v[22:23], v[0:1], v[14:15] op_sel_hi:[1,0,1] neg_lo:[1,0,0] neg_hi:[1,0,0]
	v_pk_fma_f32 v[66:67], v[24:25], v[0:1], v[16:17] op_sel_hi:[1,0,1] neg_lo:[1,0,0] neg_hi:[1,0,0]
	ds_read_b128 v[22:25], v79 offset:18816
	s_waitcnt lgkmcnt(6)
	v_pk_mul_f32 v[38:39], v[38:39], v[64:65]
	v_pk_mul_f32 v[14:15], v[32:33], v[66:67]
	v_pk_fma_f32 v[38:39], v[40:41], v[66:67], v[38:39]
	v_pk_fma_f32 v[14:15], v[30:31], v[64:65], v[14:15]
	ds_read_b128 v[30:33], v79 offset:19072
	v_add_f32_e32 v81, v14, v15
	ds_read_b128 v[14:17], v79 offset:19328
	ds_read_b128 v[26:29], v79 offset:19584
	ds_read_b128 v[18:21], v79 offset:19840
	ds_read_b32 v0, v78 offset:20096
	ds_write_b32 v99, v81 offset:12288
	v_add_f32_e32 v38, v38, v39
	s_nop 1
	v_add_f32_dpp v38, v38, v38 quad_perm:[1,0,3,2] row_mask:0xf bank_mask:0xf bound_ctrl:1
	s_nop 1
	v_add_f32_dpp v38, v38, v38 quad_perm:[2,3,0,1] row_mask:0xf bank_mask:0xf bound_ctrl:1
	v_pk_mul_f32 v[34:35], v[34:35], v[64:65]
	s_nop 0
	v_add_f32_dpp v38, v38, v38 row_half_mirror row_mask:0xf bank_mask:0xf bound_ctrl:1
	s_waitcnt lgkmcnt(8)
	v_pk_fma_f32 v[34:35], v[46:47], v[68:69], v[34:35] op_sel_hi:[1,0,1]
	v_pk_mul_f32 v[36:37], v[36:37], v[66:67]
	v_add_f32_dpp v38, v38, v38 row_mirror row_mask:0xf bank_mask:0xf bound_ctrl:1
	v_pk_fma_f32 v[36:37], v[48:49], v[68:69], v[36:37] op_sel_hi:[1,0,1]
	v_pk_fma_f32 v[66:67], v[42:43], v[38:39], v[34:35] op_sel_hi:[1,0,1] neg_lo:[1,0,0] neg_hi:[1,0,0]
	v_pk_fma_f32 v[64:65], v[44:45], v[38:39], v[36:37] op_sel_hi:[1,0,1] neg_lo:[1,0,0] neg_hi:[1,0,0]
	ds_read_b128 v[42:45], v79 offset:20160
	s_waitcnt lgkmcnt(6)
	v_pk_mul_f32 v[30:31], v[30:31], v[66:67]
	v_pk_mul_f32 v[22:23], v[22:23], v[66:67]
	v_pk_fma_f32 v[30:31], v[32:33], v[64:65], v[30:31]
	v_pk_mul_f32 v[34:35], v[52:53], v[64:65]
	v_add_f32_e32 v30, v30, v31
	s_waitcnt lgkmcnt(2)
	v_pk_fma_f32 v[22:23], v[26:27], v[0:1], v[22:23] op_sel_hi:[1,0,1]
	v_pk_fma_f32 v[34:35], v[50:51], v[66:67], v[34:35]
	ds_read_b128 v[50:53], v79 offset:20416
	v_add_f32_dpp v30, v30, v30 quad_perm:[1,0,3,2] row_mask:0xf bank_mask:0xf bound_ctrl:1
	v_add_f32_e32 v81, v34, v35
	ds_read_b128 v[34:37], v79 offset:20672
	ds_read_b128 v[46:49], v79 offset:20928
	ds_read_b128 v[38:41], v79 offset:21184
	ds_read_b32 v68, v78 offset:21440
	ds_write_b32 v99, v81 offset:13312
	v_add_f32_dpp v30, v30, v30 quad_perm:[2,3,0,1] row_mask:0xf bank_mask:0xf bound_ctrl:1
	s_nop 1
	v_add_f32_dpp v30, v30, v30 row_half_mirror row_mask:0xf bank_mask:0xf bound_ctrl:1
	s_nop 0
	s_nop 0
	v_add_f32_dpp v26, v30, v30 row_mirror row_mask:0xf bank_mask:0xf bound_ctrl:1
	v_pk_fma_f32 v[14:15], v[14:15], v[26:27], v[22:23] op_sel_hi:[1,0,1] neg_lo:[1,0,0] neg_hi:[1,0,0]
	v_pk_mul_f32 v[22:23], v[24:25], v[64:65]
	v_pk_fma_f32 v[22:23], v[28:29], v[0:1], v[22:23] op_sel_hi:[1,0,1]
	s_nop 0
	v_pk_fma_f32 v[16:17], v[16:17], v[26:27], v[22:23] op_sel_hi:[1,0,1] neg_lo:[1,0,0] neg_hi:[1,0,0]
	s_nop 0
	v_pk_mul_f32 v[20:21], v[20:21], v[16:17]
	s_nop 0
	v_pk_fma_f32 v[18:19], v[18:19], v[14:15], v[20:21]
	s_nop 0
	v_add_f32_e32 v0, v18, v19
	ds_write_b32 v99, v0 offset:14336
	s_waitcnt lgkmcnt(5)
	v_pk_mul_f32 v[18:19], v[50:51], v[14:15]
	v_pk_fma_f32 v[18:19], v[52:53], v[16:17], v[18:19]
	v_pk_mul_f32 v[16:17], v[44:45], v[16:17]
	v_add_f32_e32 v18, v18, v19
	v_pk_mul_f32 v[14:15], v[42:43], v[14:15]
	s_nop 0
	v_add_f32_dpp v18, v18, v18 quad_perm:[1,0,3,2] row_mask:0xf bank_mask:0xf bound_ctrl:1
	s_waitcnt lgkmcnt(2)
	v_pk_fma_f32 v[16:17], v[48:49], v[68:69], v[16:17] op_sel_hi:[1,0,1]
	v_add_f32_dpp v18, v18, v18 quad_perm:[2,3,0,1] row_mask:0xf bank_mask:0xf bound_ctrl:1
	v_pk_fma_f32 v[14:15], v[46:47], v[68:69], v[14:15] op_sel_hi:[1,0,1]
	s_nop 0
	v_add_f32_dpp v18, v18, v18 row_half_mirror row_mask:0xf bank_mask:0xf bound_ctrl:1
	s_nop 1
	v_add_f32_dpp v0, v18, v18 row_mirror row_mask:0xf bank_mask:0xf bound_ctrl:1
	v_pk_fma_f32 v[16:17], v[36:37], v[0:1], v[16:17] op_sel_hi:[1,0,1] neg_lo:[1,0,0] neg_hi:[1,0,0]
	v_pk_fma_f32 v[14:15], v[34:35], v[0:1], v[14:15] op_sel_hi:[1,0,1] neg_lo:[1,0,0] neg_hi:[1,0,0]
	v_pk_mul_f32 v[18:19], v[40:41], v[16:17]
	s_nop 0
	v_pk_fma_f32 v[18:19], v[38:39], v[14:15], v[18:19]
	s_nop 0
	v_add_f32_e32 v0, v18, v19
	ds_write_b32 v99, v0 offset:15360
	v_add3_u32 v18, s63, v75, v76
	s_nop 0
	s_nop 1
	s_nop 1
	s_nop 1
